# v52: prep balance - layer-1 pool_fold items moved from workgroups 64..127 to workgroups 0..63 (two each), which had ~30 us slack after the cpe move
# speedup vs baseline: 1.0092x; 1.0092x over previous
.LBB0_313:
	s_cmp_eq_u32 s18, 0x100
	s_cbranch_scc0 .Lpf_norm
	s_cmp_eq_u32 s8, 3
	s_cbranch_scc0 .Lpf_l1
	s_sub_i32 s33, s33, 64
	s_cmp_lt_u32 s33, 0x80
	s_cselect_b32 s33, s33, 0x7000
	s_cmpk_lt_i32 s33, 0x80
	s_cselect_b64 s[2:3], -1, 0
	s_branch .Lpf_norm
.Lpf_l1:
	s_cmp_eq_u32 s8, 1
	s_cbranch_scc0 .Lpf_norm
	s_cmp_lt_u32 s33, 64
	s_cselect_b32 s33, s33, 0x7000
	s_movk_i32 s27, 0x40
	s_cmpk_lt_i32 s33, 0x80
	s_cselect_b64 s[2:3], -1, 0
